# HGRN latent chunk loop: MFMA section rewritten with batched LDS reads, counted lgkmcnt waits, back-to-back MFMAs (same math)
# speedup vs baseline: 1.0081x; 1.0081x over previous
.LBB0_254:
	s_or_b64 exec, exec, s[56:57]
	s_waitcnt lgkmcnt(0)
	s_barrier
	ds_read_b128 v[206:209], v106 offset:4352
	ds_read_b128 v[222:225], v106
	ds_read_b128 v[210:213], v106 offset:4416
	ds_read_b128 v[68:71], v106 offset:64
	ds_read_b128 v[214:217], v106 offset:4480
	ds_read_b128 v[160:163], v106 offset:128
	ds_read_b128 v[218:221], v106 offset:4544
	ds_read_b128 v[168:171], v106 offset:192
	ds_read2_b64 v[186:189], v125 offset1:4
	ds_read2_b64 v[190:193], v125 offset0:8 offset1:12
	ds_read2_b64 v[194:197], v125 offset0:16 offset1:20
	ds_read2_b64 v[198:201], v125 offset0:24 offset1:28
	v_cvt_pk_bf16_f32 v72, v4, v5
	v_cvt_pk_bf16_f32 v73, v6, v7
	v_cvt_pk_bf16_f32 v74, v12, v13
	v_cvt_pk_bf16_f32 v75, v14, v15
	v_cvt_pk_bf16_f32 v76, v8, v9
	v_cvt_pk_bf16_f32 v77, v10, v11
	v_cvt_pk_bf16_f32 v78, v16, v17
	v_cvt_pk_bf16_f32 v79, v18, v19
	v_mov_b32_e32 v158, v1
	v_mov_b32_e32 v159, v1
	v_cndmask_b32_e64 v180, v127, v94, s[4:5]
	v_xad_u32 v182, v94, -2, s28
	v_add_u32_e32 v183, 1, v94
	v_cndmask_b32_e64 v182, v182, v183, s[4:5]
	v_xad_u32 v184, v94, -3, s28
	v_add_u32_e32 v185, 2, v94
	v_cndmask_b32_e64 v184, v184, v185, s[4:5]
	v_xad_u32 v202, v94, -4, s28
	v_add_u32_e32 v203, 3, v94
	v_cndmask_b32_e64 v202, v202, v203, s[4:5]
	v_ashrrev_i32_e32 v181, 31, v180
	v_lshl_add_u64 v[180:181], v[84:85], 0, v[180:181]
	v_lshlrev_b64 v[180:181], 12, v[180:181]
	v_lshl_add_u64 v[180:181], v[86:87], 0, v[180:181]
	v_ashrrev_i32_e32 v183, 31, v182
	v_lshl_add_u64 v[182:183], v[84:85], 0, v[182:183]
	v_lshlrev_b64 v[182:183], 12, v[182:183]
	v_lshl_add_u64 v[182:183], v[86:87], 0, v[182:183]
	v_ashrrev_i32_e32 v185, 31, v184
	v_lshl_add_u64 v[184:185], v[84:85], 0, v[184:185]
	v_lshlrev_b64 v[184:185], 12, v[184:185]
	v_lshl_add_u64 v[184:185], v[86:87], 0, v[184:185]
	v_ashrrev_i32_e32 v203, 31, v202
	v_lshl_add_u64 v[202:203], v[84:85], 0, v[202:203]
	v_lshlrev_b64 v[202:203], 12, v[202:203]
	v_lshl_add_u64 v[202:203], v[86:87], 0, v[202:203]
	v_add_u32_e32 v94, 16, v94
	v_add_u32_e32 v127, -16, v127
	v_add_u32_e32 v147, v107, v126
	v_add_u32_e32 v147, 0x2200, v147
	v_add_u32_e32 v205, 0x800, v147
	s_waitcnt lgkmcnt(10)
	v_mfma_f32_16x16x32_bf16 v[164:167], v[206:209], v[222:225], 0
	s_waitcnt lgkmcnt(8)
	v_mfma_f32_16x16x32_bf16 v[164:167], v[210:213], v[68:71], v[164:167]
	s_waitcnt lgkmcnt(6)
	v_mfma_f32_16x16x32_bf16 v[164:167], v[214:217], v[160:163], v[164:167]
	s_waitcnt lgkmcnt(4)
	v_mfma_f32_16x16x32_bf16 v[164:167], v[218:221], v[168:171], v[164:167]
	ds_read_b128 v[206:209], v116 offset:16896
	ds_read_b128 v[210:213], v116 offset:16960
	ds_read_b128 v[214:217], v116 offset:17024
	ds_read_b128 v[218:221], v116 offset:17088
	ds_read_b128 v[222:225], v116 offset:17152
	ds_read_b64 v[160:161], v130 offset:12800
	ds_read_b64 v[168:169], v130 offset:13312
	s_waitcnt lgkmcnt(10)
	v_mfma_f32_16x16x32_bf16 v[152:155], v[186:189], v[72:75], 0
	v_mov_b32_e32 v162, v1
	v_mfma_f32_16x16x32_bf16 v[148:151], v[186:189], v[76:79], 0
	v_mov_b32_e32 v163, v1
	v_cvt_pk_bf16_f32 v72, v20, v21
	v_cvt_pk_bf16_f32 v73, v22, v23
	v_cvt_pk_bf16_f32 v74, v28, v29
	v_cvt_pk_bf16_f32 v75, v30, v31
	v_cvt_pk_bf16_f32 v76, v24, v25
	v_cvt_pk_bf16_f32 v77, v26, v27
	v_cvt_pk_bf16_f32 v78, v32, v33
	v_cvt_pk_bf16_f32 v79, v34, v35
	v_mov_b32_e32 v170, v1
	s_waitcnt lgkmcnt(9)
	v_mfma_f32_16x16x32_bf16 v[152:155], v[190:193], v[72:75], v[152:155]
	v_mov_b32_e32 v171, v1
	v_mfma_f32_16x16x32_bf16 v[148:151], v[190:193], v[76:79], v[148:151]
	v_cvt_pk_bf16_f32 v72, v36, v37
	v_cvt_pk_bf16_f32 v73, v38, v39
	v_cvt_pk_bf16_f32 v74, v44, v45
	v_cvt_pk_bf16_f32 v75, v46, v47
	v_cvt_pk_bf16_f32 v76, v40, v41
	v_cvt_pk_bf16_f32 v77, v42, v43
	v_cvt_pk_bf16_f32 v78, v48, v49
	v_cvt_pk_bf16_f32 v79, v50, v51
	s_nop 0
	s_waitcnt lgkmcnt(8)
	v_mfma_f32_16x16x32_bf16 v[152:155], v[194:197], v[72:75], v[152:155]
	s_nop 0
	v_mfma_f32_16x16x32_bf16 v[148:151], v[194:197], v[76:79], v[148:151]
	v_cvt_pk_bf16_f32 v72, v52, v53
	v_cvt_pk_bf16_f32 v73, v54, v55
	v_cvt_pk_bf16_f32 v74, v60, v61
	v_cvt_pk_bf16_f32 v75, v62, v63
	v_cvt_pk_bf16_f32 v76, v56, v57
	v_cvt_pk_bf16_f32 v77, v58, v59
	v_cvt_pk_bf16_f32 v78, v64, v65
	v_cvt_pk_bf16_f32 v79, v66, v67
	s_nop 0
	s_waitcnt lgkmcnt(7)
	v_mfma_f32_16x16x32_bf16 v[152:155], v[198:201], v[72:75], v[152:155]
	s_nop 0
	v_mfma_f32_16x16x32_bf16 v[148:151], v[198:201], v[76:79], v[148:151]
	ds_read2_b64 v[186:189], v147 offset1:64
	ds_read2_b64 v[190:193], v147 offset0:128 offset1:192
	ds_read2_b64 v[194:197], v205 offset1:64
	ds_read2_b64 v[198:201], v205 offset0:128 offset1:192
	v_mov_b32_e32 v147, s29
	v_cndmask_b32_e64 v68, v164, v147, s[6:7]
	v_cndmask_b32_e64 v69, 0, v165, s[8:9]
	v_cndmask_b32_e64 v70, v166, 0, s[10:11]
	v_cndmask_b32_e64 v71, v167, 0, s[12:13]
	v_cndmask_b32_e64 v68, v68, v164, s[8:9]
	v_cvt_pk_bf16_f32 v156, v68, v69
	v_cvt_pk_bf16_f32 v157, v70, v71
	ds_read_b128 v[164:167], v116 offset:17216
	s_waitcnt lgkmcnt(5)
	s_nop 0
	v_mfma_f32_16x16x32_bf16 v[152:155], v[156:159], v[160:163], v[152:155]
	v_mfma_f32_16x16x32_bf16 v[148:151], v[156:159], v[168:171], v[148:151]
	v_pk_mul_f32 v[6:7], v[6:7], v[208:209]
	v_pk_mul_f32 v[4:5], v[4:5], v[206:207]
	v_pk_mul_f32 v[10:11], v[10:11], v[208:209]
	v_pk_mul_f32 v[8:9], v[8:9], v[206:207]
	v_pk_mul_f32 v[14:15], v[14:15], v[212:213]
	v_pk_mul_f32 v[12:13], v[12:13], v[210:211]
	v_pk_mul_f32 v[18:19], v[18:19], v[212:213]
	v_pk_mul_f32 v[16:17], v[16:17], v[210:211]
	global_store_dword v[180:181], v152, off
	global_store_dword v[182:183], v153, off
	global_store_dword v[184:185], v154, off
	global_store_dword v[202:203], v155, off
	global_store_dword v[180:181], v148, off offset:64
	global_store_dword v[182:183], v149, off offset:64
	global_store_dword v[184:185], v150, off offset:64
	global_store_dword v[202:203], v151, off offset:64
	v_mov_b32_e32 v202, v1
	v_mov_b32_e32 v203, v1
	ds_read_b128 v[206:209], v116 offset:17280
	ds_read_b128 v[210:213], v116 offset:17344
	s_waitcnt lgkmcnt(6)
	v_mfma_f32_16x16x32_bf16 v[4:7], v[186:189], v[160:163], v[4:7]
	v_mfma_f32_16x16x32_bf16 v[8:11], v[186:189], v[168:171], v[8:11]
	v_pk_mul_f32 v[22:23], v[22:23], v[216:217]
	v_pk_mul_f32 v[20:21], v[20:21], v[214:215]
	v_pk_mul_f32 v[26:27], v[26:27], v[216:217]
	v_pk_mul_f32 v[24:25], v[24:25], v[214:215]
	s_waitcnt lgkmcnt(5)
	v_mfma_f32_16x16x32_bf16 v[12:15], v[188:191], v[160:163], v[12:15]
	v_mfma_f32_16x16x32_bf16 v[16:19], v[188:191], v[168:171], v[16:19]
	v_pk_mul_f32 v[30:31], v[30:31], v[220:221]
	v_pk_mul_f32 v[28:29], v[28:29], v[218:219]
	v_pk_mul_f32 v[34:35], v[34:35], v[220:221]
	v_pk_mul_f32 v[32:33], v[32:33], v[218:219]
	v_mfma_f32_16x16x32_bf16 v[20:23], v[190:193], v[160:163], v[20:23]
	v_mfma_f32_16x16x32_bf16 v[24:27], v[190:193], v[168:171], v[24:27]
	v_pk_mul_f32 v[38:39], v[38:39], v[224:225]
	v_pk_mul_f32 v[36:37], v[36:37], v[222:223]
	v_pk_mul_f32 v[42:43], v[42:43], v[224:225]
	v_pk_mul_f32 v[40:41], v[40:41], v[222:223]
	s_waitcnt lgkmcnt(4)
	v_mfma_f32_16x16x32_bf16 v[28:31], v[192:195], v[160:163], v[28:31]
	v_mfma_f32_16x16x32_bf16 v[32:35], v[192:195], v[168:171], v[32:35]
	s_waitcnt lgkmcnt(2)
	v_pk_mul_f32 v[46:47], v[46:47], v[166:167]
	v_pk_mul_f32 v[44:45], v[44:45], v[164:165]
	v_pk_mul_f32 v[50:51], v[50:51], v[166:167]
	v_pk_mul_f32 v[48:49], v[48:49], v[164:165]
	v_mfma_f32_16x16x32_bf16 v[36:39], v[194:197], v[160:163], v[36:39]
	v_mfma_f32_16x16x32_bf16 v[40:43], v[194:197], v[168:171], v[40:43]
	s_waitcnt lgkmcnt(1)
	v_pk_mul_f32 v[54:55], v[54:55], v[208:209]
	v_pk_mul_f32 v[52:53], v[52:53], v[206:207]
	v_pk_mul_f32 v[58:59], v[58:59], v[208:209]
	v_pk_mul_f32 v[56:57], v[56:57], v[206:207]
	v_mfma_f32_16x16x32_bf16 v[44:47], v[196:199], v[160:163], v[44:47]
	v_mfma_f32_16x16x32_bf16 v[48:51], v[196:199], v[168:171], v[48:51]
	s_waitcnt lgkmcnt(0)
	v_pk_mul_f32 v[62:63], v[62:63], v[212:213]
	v_pk_mul_f32 v[60:61], v[60:61], v[210:211]
	v_pk_mul_f32 v[66:67], v[66:67], v[212:213]
	v_pk_mul_f32 v[64:65], v[64:65], v[210:211]
	v_mfma_f32_16x16x32_bf16 v[52:55], v[198:201], v[160:163], v[52:55]
	v_mfma_f32_16x16x32_bf16 v[56:59], v[198:201], v[168:171], v[56:59]
	v_mfma_f32_16x16x32_bf16 v[60:63], v[200:203], v[160:163], v[60:63]
	v_mfma_f32_16x16x32_bf16 v[64:67], v[200:203], v[168:171], v[64:67]
	s_waitcnt vmcnt(14)
	v_lshlrev_b32_e32 v154, 16, v146
	v_lshlrev_b32_e32 v142, 16, v142
	v_lshlrev_b32_e32 v144, 16, v144
	s_waitcnt vmcnt(8)
	v_lshlrev_b32_e32 v71, 16, v145
	v_or_b32_sdwa v68, v142, v139 dst_sel:DWORD dst_unused:UNUSED_PAD src0_sel:DWORD src1_sel:WORD_0
	v_or_b32_sdwa v69, v144, v140 dst_sel:DWORD dst_unused:UNUSED_PAD src0_sel:DWORD src1_sel:WORD_0
	v_or_b32_sdwa v70, v154, v141 dst_sel:DWORD dst_unused:UNUSED_PAD src0_sel:DWORD src1_sel:WORD_0
	v_or_b32_sdwa v71, v71, v143 dst_sel:DWORD dst_unused:UNUSED_PAD src0_sel:DWORD src1_sel:WORD_0
	s_cmp_eq_u32 s37, s53
	s_waitcnt lgkmcnt(0)
	s_barrier
	s_cbranch_scc1 .LBB0_257
